# out-proj fused epilogue: no lgkmcnt wait between a wave's own slab writes and reads (in-order LDS)
# baseline (speedup 1.0000x reference)
.LBB0_57:
	s_cmp_gt_i32 s68, 0
	s_waitcnt vmcnt(6)
	s_cselect_b32 s69, -1, 2
	s_mul_i32 s70, s68, 0x6000
	s_waitcnt lgkmcnt(0)
	s_add_i32 s69, s69, s68
	v_add_u32_e32 v135, s70, v149
	v_add_u32_e32 v0, s70, v148
	s_mulk_i32 s69, 0x6000
	v_add_u32_e32 v164, v135, v152
	s_barrier
	v_lshl_add_u64 v[180:181], v[138:139], 0, s[0:1]
	v_add_u32_e32 v159, s69, v146
	v_lshl_add_u64 v[184:185], v[136:137], 0, s[0:1]
	v_add_u32_e32 v192, s69, v147
	v_add_u32_e32 v176, v0, v152
	ds_read_b128 v[140:143], v176
	ds_read_b128 v[160:163], v164
	ds_read_b128 v[164:167], v164 offset:2048
	v_lshl_add_u64 v[182:183], v[180:181], 0, s[88:89]
	v_lshl_add_u64 v[186:187], v[184:185], 0, s[88:89]
	v_add_u32_e32 v193, 0x4000, v192
	v_lshl_add_u64 v[188:189], v[180:181], 0, s[90:91]
	v_add_u32_e32 v194, 0x400, v159
	v_lshl_add_u64 v[190:191], v[180:181], 0, s[78:79]
	v_add_u32_e32 v195, 0x800, v159
	ds_read_b128 v[168:171], v176 offset:2048
	ds_read_b128 v[172:175], v176 offset:4096
	ds_read_b128 v[176:179], v176 offset:6144
	s_waitcnt lgkmcnt(3)
	s_setprio 1
	v_mfma_f32_32x32x16_bf16 v[114:129], v[140:143], v[160:163], v[114:129]
	v_mfma_f32_32x32x16_bf16 v[98:113], v[140:143], v[164:167], v[98:113]
	v_readfirstlane_b32 s69, v159
	s_mov_b32 m0, s69
	s_nop 0
	global_load_lds_dwordx4 v[182:183], off
	s_waitcnt lgkmcnt(2)
	v_mfma_f32_32x32x16_bf16 v[82:97], v[168:171], v[160:163], v[82:97]
	v_mfma_f32_32x32x16_bf16 v[66:81], v[168:171], v[164:167], v[66:81]
	v_readfirstlane_b32 s69, v194
	s_mov_b32 m0, s69
	s_nop 0
	global_load_lds_dwordx4 v[188:189], off
	s_waitcnt lgkmcnt(1)
	v_mfma_f32_32x32x16_bf16 v[50:65], v[172:175], v[160:163], v[50:65]
	v_mfma_f32_32x32x16_bf16 v[34:49], v[172:175], v[164:167], v[34:49]
	v_readfirstlane_b32 s69, v195
	s_mov_b32 m0, s69
	s_nop 0
	global_load_lds_dwordx4 v[190:191], off
	s_waitcnt lgkmcnt(0)
	v_mfma_f32_32x32x16_bf16 v[18:33], v[176:179], v[160:163], v[18:33]
	v_mfma_f32_32x32x16_bf16 v[2:17], v[176:179], v[164:167], v[2:17]
	s_setprio 0
	v_add_u32_e32 v0, v0, v153
	v_add_u32_e32 v135, v135, v153
	ds_read_b128 v[140:143], v0
	ds_read_b128 v[160:163], v135
	ds_read_b128 v[164:167], v135 offset:2048
	ds_read_b128 v[168:171], v0 offset:2048
	ds_read_b128 v[172:175], v0 offset:4096
	ds_read_b128 v[176:179], v0 offset:6144
	s_waitcnt lgkmcnt(3)
	s_setprio 1
	v_mfma_f32_32x32x16_bf16 v[114:129], v[140:143], v[160:163], v[114:129]
	v_mfma_f32_32x32x16_bf16 v[98:113], v[140:143], v[164:167], v[98:113]
	v_add_u32_e32 v0, 0xc00, v159
	v_lshl_add_u64 v[140:141], v[180:181], 0, s[76:77]
	v_readfirstlane_b32 s69, v0
	s_mov_b32 m0, s69
	s_nop 0
	global_load_lds_dwordx4 v[140:141], off
	s_waitcnt lgkmcnt(2)
	v_mfma_f32_32x32x16_bf16 v[82:97], v[168:171], v[160:163], v[82:97]
	v_mfma_f32_32x32x16_bf16 v[66:81], v[168:171], v[164:167], v[66:81]
	v_readfirstlane_b32 s69, v193
	s_mov_b32 m0, s69
	s_nop 0
	global_load_lds_dwordx4 v[186:187], off
	s_waitcnt lgkmcnt(1)
	v_mfma_f32_32x32x16_bf16 v[50:65], v[172:175], v[160:163], v[50:65]
	v_mfma_f32_32x32x16_bf16 v[34:49], v[172:175], v[164:167], v[34:49]
	v_add_u32_e32 v0, 0x4400, v192
	v_lshl_add_u64 v[140:141], v[184:185], 0, s[90:91]
	v_readfirstlane_b32 s69, v0
	s_mov_b32 m0, s69
	s_nop 0
	global_load_lds_dwordx4 v[140:141], off
	s_waitcnt lgkmcnt(0)
	v_mfma_f32_32x32x16_bf16 v[18:33], v[176:179], v[160:163], v[18:33]
	v_mfma_f32_32x32x16_bf16 v[2:17], v[176:179], v[164:167], v[2:17]
	s_setprio 0
	s_add_i32 s69, s68, 1
	s_cmp_lt_i32 s68, 2
	s_cselect_b32 s68, s69, 0
	s_add_u32 s0, s0, 0x80
	s_addc_u32 s1, s1, 0
	s_cmpk_eq_i32 s0, 0xf00
	s_cbranch_scc0 .LBB0_57
	s_waitcnt vmcnt(6)
	s_mul_i32 s0, s68, 0x6000
	s_waitcnt lgkmcnt(0)
	v_add_u32_e32 v135, s0, v149
	v_add_u32_e32 v0, s0, v148
	v_add_u32_e32 v160, v135, v152
	s_barrier
	v_add_u32_e32 v159, v0, v152
	ds_read_b128 v[136:139], v159
	ds_read_b128 v[140:143], v160
	ds_read_b128 v[160:163], v160 offset:2048
	ds_read_b128 v[164:167], v159 offset:2048
	ds_read_b128 v[168:171], v159 offset:4096
	ds_read_b128 v[172:175], v159 offset:6144
	s_waitcnt lgkmcnt(3)
	s_setprio 1
	v_mfma_f32_32x32x16_bf16 v[114:129], v[136:139], v[140:143], v[114:129]
	v_mfma_f32_32x32x16_bf16 v[98:113], v[136:139], v[160:163], v[98:113]
	s_waitcnt lgkmcnt(2)
	v_mfma_f32_32x32x16_bf16 v[82:97], v[164:167], v[140:143], v[82:97]
	v_mfma_f32_32x32x16_bf16 v[66:81], v[164:167], v[160:163], v[66:81]
	s_waitcnt lgkmcnt(1)
	v_mfma_f32_32x32x16_bf16 v[50:65], v[168:171], v[140:143], v[50:65]
	v_mfma_f32_32x32x16_bf16 v[34:49], v[168:171], v[160:163], v[34:49]
	s_waitcnt lgkmcnt(0)
	v_mfma_f32_32x32x16_bf16 v[18:33], v[172:175], v[140:143], v[18:33]
	v_mfma_f32_32x32x16_bf16 v[2:17], v[172:175], v[160:163], v[2:17]
	s_setprio 0
	v_add_u32_e32 v0, v0, v153
	v_add_u32_e32 v135, v135, v153
	ds_read_b128 v[136:139], v0
	ds_read_b128 v[140:143], v135
	ds_read_b128 v[160:163], v135 offset:2048
	ds_read_b128 v[164:167], v0 offset:2048
	ds_read_b128 v[168:171], v0 offset:4096
	ds_read_b128 v[172:175], v0 offset:6144
	s_waitcnt lgkmcnt(3)
	s_setprio 1
	v_mfma_f32_32x32x16_bf16 v[114:129], v[136:139], v[140:143], v[114:129]
	v_mfma_f32_32x32x16_bf16 v[98:113], v[136:139], v[160:163], v[98:113]
	s_waitcnt lgkmcnt(2)
	v_mfma_f32_32x32x16_bf16 v[82:97], v[164:167], v[140:143], v[82:97]
	v_mfma_f32_32x32x16_bf16 v[66:81], v[164:167], v[160:163], v[66:81]
	s_waitcnt lgkmcnt(1)
	v_mfma_f32_32x32x16_bf16 v[50:65], v[168:171], v[140:143], v[50:65]
	v_mfma_f32_32x32x16_bf16 v[34:49], v[168:171], v[160:163], v[34:49]
	s_waitcnt lgkmcnt(0)
	v_mfma_f32_32x32x16_bf16 v[18:33], v[172:175], v[140:143], v[18:33]
	v_mfma_f32_32x32x16_bf16 v[2:17], v[172:175], v[160:163], v[2:17]
	s_setprio 0
	s_waitcnt vmcnt(0)
	s_waitcnt lgkmcnt(0)
	s_barrier
	ds_read_b128 v[136:139], v154
	ds_read_b128 v[140:143], v155
	ds_read_b128 v[160:163], v155 offset:2048
	ds_read_b128 v[164:167], v154 offset:2048
	ds_read_b128 v[168:171], v154 offset:4096
	ds_read_b128 v[172:175], v154 offset:6144
	s_waitcnt lgkmcnt(3)
	s_setprio 1
	v_mfma_f32_32x32x16_bf16 v[114:129], v[136:139], v[140:143], v[114:129]
	v_mfma_f32_32x32x16_bf16 v[98:113], v[136:139], v[160:163], v[98:113]
	s_waitcnt lgkmcnt(2)
	v_mfma_f32_32x32x16_bf16 v[82:97], v[164:167], v[140:143], v[82:97]
	v_mfma_f32_32x32x16_bf16 v[66:81], v[164:167], v[160:163], v[66:81]
	s_waitcnt lgkmcnt(1)
	v_mfma_f32_32x32x16_bf16 v[50:65], v[168:171], v[140:143], v[50:65]
	v_mfma_f32_32x32x16_bf16 v[34:49], v[168:171], v[160:163], v[34:49]
	s_waitcnt lgkmcnt(0)
	v_mfma_f32_32x32x16_bf16 v[18:33], v[172:175], v[140:143], v[18:33]
	v_mfma_f32_32x32x16_bf16 v[2:17], v[172:175], v[160:163], v[2:17]
	s_setprio 0
	ds_read_b128 v[136:139], v156
	ds_read_b128 v[140:143], v157
	ds_read_b128 v[160:163], v157 offset:2048
	ds_read_b128 v[164:167], v156 offset:2048
	ds_read_b128 v[168:171], v156 offset:4096
	ds_read_b128 v[172:175], v156 offset:6144
	s_waitcnt lgkmcnt(3)
	s_setprio 1
	v_mfma_f32_32x32x16_bf16 v[114:129], v[136:139], v[140:143], v[114:129]
	v_mfma_f32_32x32x16_bf16 v[98:113], v[136:139], v[160:163], v[98:113]
	s_waitcnt lgkmcnt(2)
	v_mfma_f32_32x32x16_bf16 v[82:97], v[164:167], v[140:143], v[82:97]
	v_mfma_f32_32x32x16_bf16 v[66:81], v[164:167], v[160:163], v[66:81]
	s_waitcnt lgkmcnt(1)
	v_mfma_f32_32x32x16_bf16 v[50:65], v[168:171], v[140:143], v[50:65]
	v_mfma_f32_32x32x16_bf16 v[34:49], v[168:171], v[160:163], v[34:49]
	s_waitcnt lgkmcnt(0)
	v_mfma_f32_32x32x16_bf16 v[18:33], v[172:175], v[140:143], v[18:33]
	v_mfma_f32_32x32x16_bf16 v[2:17], v[172:175], v[160:163], v[2:17]
	s_setprio 0
	v_add_u32_e32 v138, s29, v151
	v_or_b32_e32 v136, s31, v150
	v_ashrrev_i32_e32 v139, 31, v138
	v_lshlrev_b64 v[142:143], 10, v[138:139]
	v_ashrrev_i32_e32 v137, 31, v136
	v_lshl_add_u64 v[142:143], v[142:143], 0, v[136:137]
	s_ashr_i32 s0, s28, 4
	v_lshlrev_b64 v[160:161], 2, v[142:143]
	s_add_i32 s0, s0, s10
	v_lshl_add_u64 v[142:143], s[98:99], 0, v[160:161]
	s_movk_i32 s29, 0x2000
	s_mul_hi_i32 s1, s0, 0x3000
	s_mulk_i32 s0, 0x3000
	v_add_co_u32_e32 v162, vcc, s29, v142
	s_add_u32 s0, s4, s0
	s_nop 0
	v_addc_co_u32_e32 v163, vcc, 0, v143, vcc
	s_addc_u32 s1, s5, s1
	v_add_co_u32_e32 v164, vcc, s73, v142
	s_add_u32 s0, s0, 0x2000
	s_nop 0
	v_addc_co_u32_e32 v165, vcc, 0, v143, vcc
	s_addc_u32 s1, s1, 0
	v_add_co_u32_e32 v166, vcc, s75, v142
	v_lshl_add_u64 v[140:141], v[136:137], 2, s[0:1]
	s_nop 0
	v_addc_co_u32_e32 v167, vcc, 0, v143, vcc
	s_waitcnt vmcnt(0) lgkmcnt(0)
	s_barrier
	v_and_b32_e32 v195, 63, v200
	v_lshrrev_b32_e32 v193, 5, v195
	v_and_b32_e32 v130, 31, v195
	v_lshlrev_b32_e32 v131, 2, v193
	v_sub_u32_e32 v138, v138, v131
	v_sub_u32_e32 v136, v136, v130
	v_lshrrev_b32_e32 v131, 6, v200
	v_mul_u32_u24_e32 v131, 0x2200, v131
	v_lshlrev_b32_e32 v130, 2, v130
	s_movk_i32 s28, 0x440
	v_mad_u32_u24 v130, v193, s28, v130
	v_add_u32_e32 v130, v130, v131
	v_lshrrev_b32_e32 v193, 4, v195
	v_and_b32_e32 v192, 15, v195
	s_movk_i32 s28, 0x110
	v_mad_u32_u24 v131, v193, s28, v131
	v_lshl_add_u32 v131, v192, 4, v131
	v_lshrrev_b32_e32 v194, 6, v136
	v_add_u32_e32 v138, v138, v193
	v_lshl_add_u32 v194, v138, 4, v194
	v_lshlrev_b32_e32 v194, 2, v194
	v_lshl_add_u32 v136, v192, 2, v136
	v_lshlrev_b32_e32 v195, 2, v136
	global_load_dwordx4 v[180:183], v195, s[0:1]
	v_lshl_add_u32 v0, v138, 10, v136
	v_lshlrev_b32_e32 v0, 2, v0
	s_mov_b64 s[36:37], s[98:99]
	s_mov_b64 s[38:39], s[56:57]
	v_readlane_b32 s28, v243, 5
	v_readlane_b32 s29, v243, 6
	global_load_dwordx4 v[148:151], v0, s[36:37] nt
	s_add_u32 s36, s36, 0x4000
	s_addc_u32 s37, s37, 0
	global_load_dwordx4 v[152:155], v0, s[36:37] nt
	s_add_u32 s36, s36, 0x4000
	s_addc_u32 s37, s37, 0
	global_load_dwordx4 v[156:159], v0, s[36:37] nt
	s_add_u32 s36, s36, 0x4000
	s_addc_u32 s37, s37, 0
	global_load_dwordx4 v[160:163], v0, s[36:37] nt
	s_add_u32 s36, s36, 0x4000
	s_addc_u32 s37, s37, 0
	global_load_dwordx4 v[164:167], v0, s[36:37] nt
	s_add_u32 s36, s36, 0x4000
	s_addc_u32 s37, s37, 0
	global_load_dwordx4 v[168:171], v0, s[36:37] nt
	s_add_u32 s36, s36, 0x4000
	s_addc_u32 s37, s37, 0
	global_load_dwordx4 v[172:175], v0, s[36:37] nt
	s_add_u32 s36, s36, 0x4000
	s_addc_u32 s37, s37, 0
	global_load_dwordx4 v[176:179], v0, s[36:37] nt
	s_add_u32 s36, s36, 0x4000
	s_addc_u32 s37, s37, 0
	ds_write2_b32 v130, v114, v98 offset0:0 offset1:32
	ds_write2_b32 v130, v115, v99 offset0:68 offset1:100
	ds_write2_b32 v130, v116, v100 offset0:136 offset1:168
	ds_write2_b32 v130, v117, v101 offset0:204 offset1:236
	v_add_u32_e32 v130, 0x880, v130
	ds_write2_b32 v130, v118, v102 offset0:0 offset1:32
	ds_write2_b32 v130, v119, v103 offset0:68 offset1:100
	ds_write2_b32 v130, v120, v104 offset0:136 offset1:168
	ds_write2_b32 v130, v121, v105 offset0:204 offset1:236
	v_add_u32_e32 v130, 0x880, v130
	ds_write2_b32 v130, v122, v106 offset0:0 offset1:32
	ds_write2_b32 v130, v123, v107 offset0:68 offset1:100
	ds_write2_b32 v130, v124, v108 offset0:136 offset1:168
	ds_write2_b32 v130, v125, v109 offset0:204 offset1:236
	v_add_u32_e32 v130, 0x880, v130
	ds_write2_b32 v130, v126, v110 offset0:0 offset1:32
	ds_write2_b32 v130, v127, v111 offset0:68 offset1:100
	ds_write2_b32 v130, v128, v112 offset0:136 offset1:168
	ds_write2_b32 v130, v129, v113 offset0:204 offset1:236
	v_subrev_u32_e32 v130, 0x1980, v130
	ds_read_b128 v[98:101], v131
	ds_read_b128 v[102:105], v131 offset:1088
	ds_read_b128 v[106:109], v131 offset:2176
	ds_read_b128 v[110:113], v131 offset:3264
	ds_read_b128 v[114:117], v131 offset:4352
	ds_read_b128 v[118:121], v131 offset:5440
	ds_read_b128 v[122:125], v131 offset:6528
	ds_read_b128 v[126:129], v131 offset:7616
	s_waitcnt vmcnt(0) lgkmcnt(0)
	v_fma_f32 v98, v98, v180, v148
	v_fma_f32 v99, v99, v181, v149
	v_fma_f32 v100, v100, v182, v150
	v_fma_f32 v101, v101, v183, v151
	global_store_dwordx4 v0, v[98:101], s[38:39] nt
	s_add_u32 s38, s38, 0x4000
	s_addc_u32 s39, s39, 0
	v_mul_f32_e32 v184, v98, v98
	v_fmac_f32_e32 v184, v99, v99
	v_fmac_f32_e32 v184, v100, v100
	v_fmac_f32_e32 v184, v101, v101
	v_fma_f32 v102, v102, v180, v152
	v_fma_f32 v103, v103, v181, v153
	v_fma_f32 v104, v104, v182, v154
	v_fma_f32 v105, v105, v183, v155
	global_store_dwordx4 v0, v[102:105], s[38:39] nt
	s_add_u32 s38, s38, 0x4000
	s_addc_u32 s39, s39, 0
	v_mul_f32_e32 v185, v102, v102
	v_fmac_f32_e32 v185, v103, v103
	v_fmac_f32_e32 v185, v104, v104
	v_fmac_f32_e32 v185, v105, v105
	v_fma_f32 v106, v106, v180, v156
	v_fma_f32 v107, v107, v181, v157
	v_fma_f32 v108, v108, v182, v158
	v_fma_f32 v109, v109, v183, v159
	global_store_dwordx4 v0, v[106:109], s[38:39] nt
	s_add_u32 s38, s38, 0x4000
	s_addc_u32 s39, s39, 0
	v_mul_f32_e32 v186, v106, v106
	v_fmac_f32_e32 v186, v107, v107
	v_fmac_f32_e32 v186, v108, v108
	v_fmac_f32_e32 v186, v109, v109
	v_fma_f32 v110, v110, v180, v160
	v_fma_f32 v111, v111, v181, v161
	v_fma_f32 v112, v112, v182, v162
	v_fma_f32 v113, v113, v183, v163
	global_store_dwordx4 v0, v[110:113], s[38:39] nt
	s_add_u32 s38, s38, 0x4000
	s_addc_u32 s39, s39, 0
	v_mul_f32_e32 v187, v110, v110
	v_fmac_f32_e32 v187, v111, v111
	v_fmac_f32_e32 v187, v112, v112
	v_fmac_f32_e32 v187, v113, v113
	v_fma_f32 v114, v114, v180, v164
	v_fma_f32 v115, v115, v181, v165
	v_fma_f32 v116, v116, v182, v166
	v_fma_f32 v117, v117, v183, v167
	global_store_dwordx4 v0, v[114:117], s[38:39] nt
	s_add_u32 s38, s38, 0x4000
	s_addc_u32 s39, s39, 0
	v_mul_f32_e32 v188, v114, v114
	v_fmac_f32_e32 v188, v115, v115
	v_fmac_f32_e32 v188, v116, v116
	v_fmac_f32_e32 v188, v117, v117
	v_fma_f32 v118, v118, v180, v168
	v_fma_f32 v119, v119, v181, v169
	v_fma_f32 v120, v120, v182, v170
	v_fma_f32 v121, v121, v183, v171
	global_store_dwordx4 v0, v[118:121], s[38:39] nt
	s_add_u32 s38, s38, 0x4000
	s_addc_u32 s39, s39, 0
	v_mul_f32_e32 v189, v118, v118
	v_fmac_f32_e32 v189, v119, v119
	v_fmac_f32_e32 v189, v120, v120
	v_fmac_f32_e32 v189, v121, v121
	v_fma_f32 v122, v122, v180, v172
	v_fma_f32 v123, v123, v181, v173
	v_fma_f32 v124, v124, v182, v174
	v_fma_f32 v125, v125, v183, v175
	global_store_dwordx4 v0, v[122:125], s[38:39] nt
	s_add_u32 s38, s38, 0x4000
	s_addc_u32 s39, s39, 0
	v_mul_f32_e32 v190, v122, v122
	v_fmac_f32_e32 v190, v123, v123
	v_fmac_f32_e32 v190, v124, v124
	v_fmac_f32_e32 v190, v125, v125
	v_fma_f32 v126, v126, v180, v176
	v_fma_f32 v127, v127, v181, v177
	v_fma_f32 v128, v128, v182, v178
	v_fma_f32 v129, v129, v183, v179
	global_store_dwordx4 v0, v[126:129], s[38:39] nt
	s_add_u32 s38, s38, 0x4000
	s_addc_u32 s39, s39, 0
	v_mul_f32_e32 v191, v126, v126
	v_fmac_f32_e32 v191, v127, v127
	v_fmac_f32_e32 v191, v128, v128
	v_fmac_f32_e32 v191, v129, v129
	global_load_dwordx4 v[148:151], v0, s[36:37] nt
	s_add_u32 s36, s36, 0x4000
	s_addc_u32 s37, s37, 0
	global_load_dwordx4 v[152:155], v0, s[36:37] nt
	s_add_u32 s36, s36, 0x4000
	s_addc_u32 s37, s37, 0
	global_load_dwordx4 v[156:159], v0, s[36:37] nt
	s_add_u32 s36, s36, 0x4000
	s_addc_u32 s37, s37, 0
	global_load_dwordx4 v[160:163], v0, s[36:37] nt
	s_add_u32 s36, s36, 0x4000
	s_addc_u32 s37, s37, 0
	global_load_dwordx4 v[164:167], v0, s[36:37] nt
	s_add_u32 s36, s36, 0x4000
	s_addc_u32 s37, s37, 0
	global_load_dwordx4 v[168:171], v0, s[36:37] nt
	s_add_u32 s36, s36, 0x4000
	s_addc_u32 s37, s37, 0
	global_load_dwordx4 v[172:175], v0, s[36:37] nt
	s_add_u32 s36, s36, 0x4000
	s_addc_u32 s37, s37, 0
	global_load_dwordx4 v[176:179], v0, s[36:37] nt
	s_add_u32 s36, s36, 0x4000
	s_addc_u32 s37, s37, 0
	v_add_f32_dpp v184, v184, v184 quad_perm:[1,0,3,2] row_mask:0xf bank_mask:0xf
	v_add_f32_dpp v185, v185, v185 quad_perm:[1,0,3,2] row_mask:0xf bank_mask:0xf
	v_add_f32_dpp v186, v186, v186 quad_perm:[1,0,3,2] row_mask:0xf bank_mask:0xf
	v_add_f32_dpp v187, v187, v187 quad_perm:[1,0,3,2] row_mask:0xf bank_mask:0xf
	v_add_f32_dpp v188, v188, v188 quad_perm:[1,0,3,2] row_mask:0xf bank_mask:0xf
	v_add_f32_dpp v189, v189, v189 quad_perm:[1,0,3,2] row_mask:0xf bank_mask:0xf
	v_add_f32_dpp v190, v190, v190 quad_perm:[1,0,3,2] row_mask:0xf bank_mask:0xf
	v_add_f32_dpp v191, v191, v191 quad_perm:[1,0,3,2] row_mask:0xf bank_mask:0xf
	v_add_f32_dpp v184, v184, v184 quad_perm:[2,3,0,1] row_mask:0xf bank_mask:0xf
	v_add_f32_dpp v185, v185, v185 quad_perm:[2,3,0,1] row_mask:0xf bank_mask:0xf
	v_add_f32_dpp v186, v186, v186 quad_perm:[2,3,0,1] row_mask:0xf bank_mask:0xf
	v_add_f32_dpp v187, v187, v187 quad_perm:[2,3,0,1] row_mask:0xf bank_mask:0xf
	v_add_f32_dpp v188, v188, v188 quad_perm:[2,3,0,1] row_mask:0xf bank_mask:0xf
	v_add_f32_dpp v189, v189, v189 quad_perm:[2,3,0,1] row_mask:0xf bank_mask:0xf
	v_add_f32_dpp v190, v190, v190 quad_perm:[2,3,0,1] row_mask:0xf bank_mask:0xf
	v_add_f32_dpp v191, v191, v191 quad_perm:[2,3,0,1] row_mask:0xf bank_mask:0xf
	v_add_f32_dpp v184, v184, v184 row_half_mirror row_mask:0xf bank_mask:0xf
	v_add_f32_dpp v185, v185, v185 row_half_mirror row_mask:0xf bank_mask:0xf
	v_add_f32_dpp v186, v186, v186 row_half_mirror row_mask:0xf bank_mask:0xf
	v_add_f32_dpp v187, v187, v187 row_half_mirror row_mask:0xf bank_mask:0xf
	v_add_f32_dpp v188, v188, v188 row_half_mirror row_mask:0xf bank_mask:0xf
	v_add_f32_dpp v189, v189, v189 row_half_mirror row_mask:0xf bank_mask:0xf
	v_add_f32_dpp v190, v190, v190 row_half_mirror row_mask:0xf bank_mask:0xf
	v_add_f32_dpp v191, v191, v191 row_half_mirror row_mask:0xf bank_mask:0xf
	v_add_f32_dpp v184, v184, v184 row_mirror row_mask:0xf bank_mask:0xf
	v_add_f32_dpp v185, v185, v185 row_mirror row_mask:0xf bank_mask:0xf
	v_add_f32_dpp v186, v186, v186 row_mirror row_mask:0xf bank_mask:0xf
	v_add_f32_dpp v187, v187, v187 row_mirror row_mask:0xf bank_mask:0xf
	v_add_f32_dpp v188, v188, v188 row_mirror row_mask:0xf bank_mask:0xf
	v_add_f32_dpp v189, v189, v189 row_mirror row_mask:0xf bank_mask:0xf
	v_add_f32_dpp v190, v190, v190 row_mirror row_mask:0xf bank_mask:0xf
	v_add_f32_dpp v191, v191, v191 row_mirror row_mask:0xf bank_mask:0xf
	v_cmp_eq_u32_e32 vcc, 0, v192
	s_and_saveexec_b64 s[0:1], vcc
	global_store_dword v194, v184, s[28:29]
	s_add_u32 s28, s28, 0x100
	s_addc_u32 s29, s29, 0
	global_store_dword v194, v185, s[28:29]
	s_add_u32 s28, s28, 0x100
	s_addc_u32 s29, s29, 0
	global_store_dword v194, v186, s[28:29]
	s_add_u32 s28, s28, 0x100
	s_addc_u32 s29, s29, 0
	global_store_dword v194, v187, s[28:29]
	s_add_u32 s28, s28, 0x100
	s_addc_u32 s29, s29, 0
	global_store_dword v194, v188, s[28:29]
	s_add_u32 s28, s28, 0x100
	s_addc_u32 s29, s29, 0
	global_store_dword v194, v189, s[28:29]
	s_add_u32 s28, s28, 0x100
	s_addc_u32 s29, s29, 0
	global_store_dword v194, v190, s[28:29]
	s_add_u32 s28, s28, 0x100
	s_addc_u32 s29, s29, 0
	global_store_dword v194, v191, s[28:29]
	s_add_u32 s28, s28, 0x100
	s_addc_u32 s29, s29, 0
	s_or_b64 exec, exec, s[0:1]
	ds_write2_b32 v130, v82, v66 offset0:0 offset1:32
	ds_write2_b32 v130, v83, v67 offset0:68 offset1:100
	ds_write2_b32 v130, v84, v68 offset0:136 offset1:168
	ds_write2_b32 v130, v85, v69 offset0:204 offset1:236
	v_add_u32_e32 v130, 0x880, v130
	ds_write2_b32 v130, v86, v70 offset0:0 offset1:32
	ds_write2_b32 v130, v87, v71 offset0:68 offset1:100
	ds_write2_b32 v130, v88, v72 offset0:136 offset1:168
	ds_write2_b32 v130, v89, v73 offset0:204 offset1:236
	v_add_u32_e32 v130, 0x880, v130
	ds_write2_b32 v130, v90, v74 offset0:0 offset1:32
	ds_write2_b32 v130, v91, v75 offset0:68 offset1:100
	ds_write2_b32 v130, v92, v76 offset0:136 offset1:168
	ds_write2_b32 v130, v93, v77 offset0:204 offset1:236
	v_add_u32_e32 v130, 0x880, v130
	ds_write2_b32 v130, v94, v78 offset0:0 offset1:32
	ds_write2_b32 v130, v95, v79 offset0:68 offset1:100
	ds_write2_b32 v130, v96, v80 offset0:136 offset1:168
	ds_write2_b32 v130, v97, v81 offset0:204 offset1:236
	v_subrev_u32_e32 v130, 0x1980, v130
	ds_read_b128 v[66:69], v131
	ds_read_b128 v[70:73], v131 offset:1088
	ds_read_b128 v[74:77], v131 offset:2176
	ds_read_b128 v[78:81], v131 offset:3264
	ds_read_b128 v[82:85], v131 offset:4352
	ds_read_b128 v[86:89], v131 offset:5440
	ds_read_b128 v[90:93], v131 offset:6528
	ds_read_b128 v[94:97], v131 offset:7616
	s_waitcnt vmcnt(8) lgkmcnt(0)
	v_fma_f32 v66, v66, v180, v148
	v_fma_f32 v67, v67, v181, v149
	v_fma_f32 v68, v68, v182, v150
	v_fma_f32 v69, v69, v183, v151
	global_store_dwordx4 v0, v[66:69], s[38:39] nt
	s_add_u32 s38, s38, 0x4000
	s_addc_u32 s39, s39, 0
	v_mul_f32_e32 v184, v66, v66
	v_fmac_f32_e32 v184, v67, v67
	v_fmac_f32_e32 v184, v68, v68
	v_fmac_f32_e32 v184, v69, v69
	v_fma_f32 v70, v70, v180, v152
	v_fma_f32 v71, v71, v181, v153
	v_fma_f32 v72, v72, v182, v154
	v_fma_f32 v73, v73, v183, v155
	global_store_dwordx4 v0, v[70:73], s[38:39] nt
	s_add_u32 s38, s38, 0x4000
	s_addc_u32 s39, s39, 0
	v_mul_f32_e32 v185, v70, v70
	v_fmac_f32_e32 v185, v71, v71
	v_fmac_f32_e32 v185, v72, v72
	v_fmac_f32_e32 v185, v73, v73
	v_fma_f32 v74, v74, v180, v156
	v_fma_f32 v75, v75, v181, v157
	v_fma_f32 v76, v76, v182, v158
	v_fma_f32 v77, v77, v183, v159
	global_store_dwordx4 v0, v[74:77], s[38:39] nt
	s_add_u32 s38, s38, 0x4000
	s_addc_u32 s39, s39, 0
	v_mul_f32_e32 v186, v74, v74
	v_fmac_f32_e32 v186, v75, v75
	v_fmac_f32_e32 v186, v76, v76
	v_fmac_f32_e32 v186, v77, v77
	v_fma_f32 v78, v78, v180, v160
	v_fma_f32 v79, v79, v181, v161
	v_fma_f32 v80, v80, v182, v162
	v_fma_f32 v81, v81, v183, v163
	global_store_dwordx4 v0, v[78:81], s[38:39] nt
	s_add_u32 s38, s38, 0x4000
	s_addc_u32 s39, s39, 0
	v_mul_f32_e32 v187, v78, v78
	v_fmac_f32_e32 v187, v79, v79
	v_fmac_f32_e32 v187, v80, v80
	v_fmac_f32_e32 v187, v81, v81
	v_fma_f32 v82, v82, v180, v164
	v_fma_f32 v83, v83, v181, v165
	v_fma_f32 v84, v84, v182, v166
	v_fma_f32 v85, v85, v183, v167
	global_store_dwordx4 v0, v[82:85], s[38:39] nt
	s_add_u32 s38, s38, 0x4000
	s_addc_u32 s39, s39, 0
	v_mul_f32_e32 v188, v82, v82
	v_fmac_f32_e32 v188, v83, v83
	v_fmac_f32_e32 v188, v84, v84
	v_fmac_f32_e32 v188, v85, v85
	v_fma_f32 v86, v86, v180, v168
	v_fma_f32 v87, v87, v181, v169
	v_fma_f32 v88, v88, v182, v170
	v_fma_f32 v89, v89, v183, v171
	global_store_dwordx4 v0, v[86:89], s[38:39] nt
	s_add_u32 s38, s38, 0x4000
	s_addc_u32 s39, s39, 0
	v_mul_f32_e32 v189, v86, v86
	v_fmac_f32_e32 v189, v87, v87
	v_fmac_f32_e32 v189, v88, v88
	v_fmac_f32_e32 v189, v89, v89
	v_fma_f32 v90, v90, v180, v172
	v_fma_f32 v91, v91, v181, v173
	v_fma_f32 v92, v92, v182, v174
	v_fma_f32 v93, v93, v183, v175
	global_store_dwordx4 v0, v[90:93], s[38:39] nt
	s_add_u32 s38, s38, 0x4000
	s_addc_u32 s39, s39, 0
	v_mul_f32_e32 v190, v90, v90
	v_fmac_f32_e32 v190, v91, v91
	v_fmac_f32_e32 v190, v92, v92
	v_fmac_f32_e32 v190, v93, v93
	v_fma_f32 v94, v94, v180, v176
	v_fma_f32 v95, v95, v181, v177
	v_fma_f32 v96, v96, v182, v178
	v_fma_f32 v97, v97, v183, v179
	global_store_dwordx4 v0, v[94:97], s[38:39] nt
	s_add_u32 s38, s38, 0x4000
	s_addc_u32 s39, s39, 0
	v_mul_f32_e32 v191, v94, v94
	v_fmac_f32_e32 v191, v95, v95
	v_fmac_f32_e32 v191, v96, v96
	v_fmac_f32_e32 v191, v97, v97
	global_load_dwordx4 v[148:151], v0, s[36:37] nt
	s_add_u32 s36, s36, 0x4000
	s_addc_u32 s37, s37, 0
	global_load_dwordx4 v[152:155], v0, s[36:37] nt
	s_add_u32 s36, s36, 0x4000
	s_addc_u32 s37, s37, 0
	global_load_dwordx4 v[156:159], v0, s[36:37] nt
	s_add_u32 s36, s36, 0x4000
	s_addc_u32 s37, s37, 0
	global_load_dwordx4 v[160:163], v0, s[36:37] nt
	s_add_u32 s36, s36, 0x4000
	s_addc_u32 s37, s37, 0
	global_load_dwordx4 v[164:167], v0, s[36:37] nt
	s_add_u32 s36, s36, 0x4000
	s_addc_u32 s37, s37, 0
	global_load_dwordx4 v[168:171], v0, s[36:37] nt
	s_add_u32 s36, s36, 0x4000
	s_addc_u32 s37, s37, 0
	global_load_dwordx4 v[172:175], v0, s[36:37] nt
	s_add_u32 s36, s36, 0x4000
	s_addc_u32 s37, s37, 0
	global_load_dwordx4 v[176:179], v0, s[36:37] nt
	s_add_u32 s36, s36, 0x4000
	s_addc_u32 s37, s37, 0
	v_add_f32_dpp v184, v184, v184 quad_perm:[1,0,3,2] row_mask:0xf bank_mask:0xf
	v_add_f32_dpp v185, v185, v185 quad_perm:[1,0,3,2] row_mask:0xf bank_mask:0xf
	v_add_f32_dpp v186, v186, v186 quad_perm:[1,0,3,2] row_mask:0xf bank_mask:0xf
	v_add_f32_dpp v187, v187, v187 quad_perm:[1,0,3,2] row_mask:0xf bank_mask:0xf
	v_add_f32_dpp v188, v188, v188 quad_perm:[1,0,3,2] row_mask:0xf bank_mask:0xf
	v_add_f32_dpp v189, v189, v189 quad_perm:[1,0,3,2] row_mask:0xf bank_mask:0xf
	v_add_f32_dpp v190, v190, v190 quad_perm:[1,0,3,2] row_mask:0xf bank_mask:0xf
	v_add_f32_dpp v191, v191, v191 quad_perm:[1,0,3,2] row_mask:0xf bank_mask:0xf
	v_add_f32_dpp v184, v184, v184 quad_perm:[2,3,0,1] row_mask:0xf bank_mask:0xf
	v_add_f32_dpp v185, v185, v185 quad_perm:[2,3,0,1] row_mask:0xf bank_mask:0xf
	v_add_f32_dpp v186, v186, v186 quad_perm:[2,3,0,1] row_mask:0xf bank_mask:0xf
	v_add_f32_dpp v187, v187, v187 quad_perm:[2,3,0,1] row_mask:0xf bank_mask:0xf
	v_add_f32_dpp v188, v188, v188 quad_perm:[2,3,0,1] row_mask:0xf bank_mask:0xf
	v_add_f32_dpp v189, v189, v189 quad_perm:[2,3,0,1] row_mask:0xf bank_mask:0xf
	v_add_f32_dpp v190, v190, v190 quad_perm:[2,3,0,1] row_mask:0xf bank_mask:0xf
	v_add_f32_dpp v191, v191, v191 quad_perm:[2,3,0,1] row_mask:0xf bank_mask:0xf
	v_add_f32_dpp v184, v184, v184 row_half_mirror row_mask:0xf bank_mask:0xf
	v_add_f32_dpp v185, v185, v185 row_half_mirror row_mask:0xf bank_mask:0xf
	v_add_f32_dpp v186, v186, v186 row_half_mirror row_mask:0xf bank_mask:0xf
	v_add_f32_dpp v187, v187, v187 row_half_mirror row_mask:0xf bank_mask:0xf
	v_add_f32_dpp v188, v188, v188 row_half_mirror row_mask:0xf bank_mask:0xf
	v_add_f32_dpp v189, v189, v189 row_half_mirror row_mask:0xf bank_mask:0xf
	v_add_f32_dpp v190, v190, v190 row_half_mirror row_mask:0xf bank_mask:0xf
	v_add_f32_dpp v191, v191, v191 row_half_mirror row_mask:0xf bank_mask:0xf
	v_add_f32_dpp v184, v184, v184 row_mirror row_mask:0xf bank_mask:0xf
	v_add_f32_dpp v185, v185, v185 row_mirror row_mask:0xf bank_mask:0xf
	v_add_f32_dpp v186, v186, v186 row_mirror row_mask:0xf bank_mask:0xf
	v_add_f32_dpp v187, v187, v187 row_mirror row_mask:0xf bank_mask:0xf
	v_add_f32_dpp v188, v188, v188 row_mirror row_mask:0xf bank_mask:0xf
	v_add_f32_dpp v189, v189, v189 row_mirror row_mask:0xf bank_mask:0xf
	v_add_f32_dpp v190, v190, v190 row_mirror row_mask:0xf bank_mask:0xf
	v_add_f32_dpp v191, v191, v191 row_mirror row_mask:0xf bank_mask:0xf
	v_cmp_eq_u32_e32 vcc, 0, v192
	s_and_saveexec_b64 s[0:1], vcc
	global_store_dword v194, v184, s[28:29]
	s_add_u32 s28, s28, 0x100
	s_addc_u32 s29, s29, 0
	global_store_dword v194, v185, s[28:29]
	s_add_u32 s28, s28, 0x100
	s_addc_u32 s29, s29, 0
	global_store_dword v194, v186, s[28:29]
	s_add_u32 s28, s28, 0x100
	s_addc_u32 s29, s29, 0
	global_store_dword v194, v187, s[28:29]
	s_add_u32 s28, s28, 0x100
	s_addc_u32 s29, s29, 0
	global_store_dword v194, v188, s[28:29]
	s_add_u32 s28, s28, 0x100
	s_addc_u32 s29, s29, 0
	global_store_dword v194, v189, s[28:29]
	s_add_u32 s28, s28, 0x100
	s_addc_u32 s29, s29, 0
	global_store_dword v194, v190, s[28:29]
	s_add_u32 s28, s28, 0x100
	s_addc_u32 s29, s29, 0
	global_store_dword v194, v191, s[28:29]
	s_add_u32 s28, s28, 0x100
	s_addc_u32 s29, s29, 0
	s_or_b64 exec, exec, s[0:1]
	ds_write2_b32 v130, v50, v34 offset0:0 offset1:32
	ds_write2_b32 v130, v51, v35 offset0:68 offset1:100
	ds_write2_b32 v130, v52, v36 offset0:136 offset1:168
	ds_write2_b32 v130, v53, v37 offset0:204 offset1:236
	v_add_u32_e32 v130, 0x880, v130
	ds_write2_b32 v130, v54, v38 offset0:0 offset1:32
	ds_write2_b32 v130, v55, v39 offset0:68 offset1:100
	ds_write2_b32 v130, v56, v40 offset0:136 offset1:168
	ds_write2_b32 v130, v57, v41 offset0:204 offset1:236
	v_add_u32_e32 v130, 0x880, v130
	ds_write2_b32 v130, v58, v42 offset0:0 offset1:32
	ds_write2_b32 v130, v59, v43 offset0:68 offset1:100
	ds_write2_b32 v130, v60, v44 offset0:136 offset1:168
	ds_write2_b32 v130, v61, v45 offset0:204 offset1:236
	v_add_u32_e32 v130, 0x880, v130
	ds_write2_b32 v130, v62, v46 offset0:0 offset1:32
	ds_write2_b32 v130, v63, v47 offset0:68 offset1:100
	ds_write2_b32 v130, v64, v48 offset0:136 offset1:168
	ds_write2_b32 v130, v65, v49 offset0:204 offset1:236
	v_subrev_u32_e32 v130, 0x1980, v130
	ds_read_b128 v[34:37], v131
	ds_read_b128 v[38:41], v131 offset:1088
	ds_read_b128 v[42:45], v131 offset:2176
	ds_read_b128 v[46:49], v131 offset:3264
	ds_read_b128 v[50:53], v131 offset:4352
	ds_read_b128 v[54:57], v131 offset:5440
	ds_read_b128 v[58:61], v131 offset:6528
	ds_read_b128 v[62:65], v131 offset:7616
	s_waitcnt vmcnt(8) lgkmcnt(0)
	v_fma_f32 v34, v34, v180, v148
	v_fma_f32 v35, v35, v181, v149
	v_fma_f32 v36, v36, v182, v150
	v_fma_f32 v37, v37, v183, v151
	global_store_dwordx4 v0, v[34:37], s[38:39] nt
	s_add_u32 s38, s38, 0x4000
	s_addc_u32 s39, s39, 0
	v_mul_f32_e32 v184, v34, v34
	v_fmac_f32_e32 v184, v35, v35
	v_fmac_f32_e32 v184, v36, v36
	v_fmac_f32_e32 v184, v37, v37
	v_fma_f32 v38, v38, v180, v152
	v_fma_f32 v39, v39, v181, v153
	v_fma_f32 v40, v40, v182, v154
	v_fma_f32 v41, v41, v183, v155
	global_store_dwordx4 v0, v[38:41], s[38:39] nt
	s_add_u32 s38, s38, 0x4000
	s_addc_u32 s39, s39, 0
	v_mul_f32_e32 v185, v38, v38
	v_fmac_f32_e32 v185, v39, v39
	v_fmac_f32_e32 v185, v40, v40
	v_fmac_f32_e32 v185, v41, v41
	v_fma_f32 v42, v42, v180, v156
	v_fma_f32 v43, v43, v181, v157
	v_fma_f32 v44, v44, v182, v158
	v_fma_f32 v45, v45, v183, v159
	global_store_dwordx4 v0, v[42:45], s[38:39] nt
	s_add_u32 s38, s38, 0x4000
	s_addc_u32 s39, s39, 0
	v_mul_f32_e32 v186, v42, v42
	v_fmac_f32_e32 v186, v43, v43
	v_fmac_f32_e32 v186, v44, v44
	v_fmac_f32_e32 v186, v45, v45
	v_fma_f32 v46, v46, v180, v160
	v_fma_f32 v47, v47, v181, v161
	v_fma_f32 v48, v48, v182, v162
	v_fma_f32 v49, v49, v183, v163
	global_store_dwordx4 v0, v[46:49], s[38:39] nt
	s_add_u32 s38, s38, 0x4000
	s_addc_u32 s39, s39, 0
	v_mul_f32_e32 v187, v46, v46
	v_fmac_f32_e32 v187, v47, v47
	v_fmac_f32_e32 v187, v48, v48
	v_fmac_f32_e32 v187, v49, v49
	v_fma_f32 v50, v50, v180, v164
	v_fma_f32 v51, v51, v181, v165
	v_fma_f32 v52, v52, v182, v166
	v_fma_f32 v53, v53, v183, v167
	global_store_dwordx4 v0, v[50:53], s[38:39] nt
	s_add_u32 s38, s38, 0x4000
	s_addc_u32 s39, s39, 0
	v_mul_f32_e32 v188, v50, v50
	v_fmac_f32_e32 v188, v51, v51
	v_fmac_f32_e32 v188, v52, v52
	v_fmac_f32_e32 v188, v53, v53
	v_fma_f32 v54, v54, v180, v168
	v_fma_f32 v55, v55, v181, v169
	v_fma_f32 v56, v56, v182, v170
	v_fma_f32 v57, v57, v183, v171
	global_store_dwordx4 v0, v[54:57], s[38:39] nt
	s_add_u32 s38, s38, 0x4000
	s_addc_u32 s39, s39, 0
	v_mul_f32_e32 v189, v54, v54
	v_fmac_f32_e32 v189, v55, v55
	v_fmac_f32_e32 v189, v56, v56
	v_fmac_f32_e32 v189, v57, v57
	v_fma_f32 v58, v58, v180, v172
	v_fma_f32 v59, v59, v181, v173
	v_fma_f32 v60, v60, v182, v174
	v_fma_f32 v61, v61, v183, v175
	global_store_dwordx4 v0, v[58:61], s[38:39] nt
	s_add_u32 s38, s38, 0x4000
	s_addc_u32 s39, s39, 0
	v_mul_f32_e32 v190, v58, v58
	v_fmac_f32_e32 v190, v59, v59
	v_fmac_f32_e32 v190, v60, v60
	v_fmac_f32_e32 v190, v61, v61
	v_fma_f32 v62, v62, v180, v176
	v_fma_f32 v63, v63, v181, v177
	v_fma_f32 v64, v64, v182, v178
	v_fma_f32 v65, v65, v183, v179
	global_store_dwordx4 v0, v[62:65], s[38:39] nt
	s_add_u32 s38, s38, 0x4000
	s_addc_u32 s39, s39, 0
	v_mul_f32_e32 v191, v62, v62
	v_fmac_f32_e32 v191, v63, v63
	v_fmac_f32_e32 v191, v64, v64
	v_fmac_f32_e32 v191, v65, v65
	global_load_dwordx4 v[148:151], v0, s[36:37] nt
	s_add_u32 s36, s36, 0x4000
	s_addc_u32 s37, s37, 0
	global_load_dwordx4 v[152:155], v0, s[36:37] nt
	s_add_u32 s36, s36, 0x4000
	s_addc_u32 s37, s37, 0
	global_load_dwordx4 v[156:159], v0, s[36:37] nt
	s_add_u32 s36, s36, 0x4000
	s_addc_u32 s37, s37, 0
	global_load_dwordx4 v[160:163], v0, s[36:37] nt
	s_add_u32 s36, s36, 0x4000
	s_addc_u32 s37, s37, 0
	global_load_dwordx4 v[164:167], v0, s[36:37] nt
	s_add_u32 s36, s36, 0x4000
	s_addc_u32 s37, s37, 0
	global_load_dwordx4 v[168:171], v0, s[36:37] nt
	s_add_u32 s36, s36, 0x4000
	s_addc_u32 s37, s37, 0
	global_load_dwordx4 v[172:175], v0, s[36:37] nt
	s_add_u32 s36, s36, 0x4000
	s_addc_u32 s37, s37, 0
	global_load_dwordx4 v[176:179], v0, s[36:37] nt
	s_add_u32 s36, s36, 0x4000
	s_addc_u32 s37, s37, 0
	v_add_f32_dpp v184, v184, v184 quad_perm:[1,0,3,2] row_mask:0xf bank_mask:0xf
	v_add_f32_dpp v185, v185, v185 quad_perm:[1,0,3,2] row_mask:0xf bank_mask:0xf
	v_add_f32_dpp v186, v186, v186 quad_perm:[1,0,3,2] row_mask:0xf bank_mask:0xf
	v_add_f32_dpp v187, v187, v187 quad_perm:[1,0,3,2] row_mask:0xf bank_mask:0xf
	v_add_f32_dpp v188, v188, v188 quad_perm:[1,0,3,2] row_mask:0xf bank_mask:0xf
	v_add_f32_dpp v189, v189, v189 quad_perm:[1,0,3,2] row_mask:0xf bank_mask:0xf
	v_add_f32_dpp v190, v190, v190 quad_perm:[1,0,3,2] row_mask:0xf bank_mask:0xf
	v_add_f32_dpp v191, v191, v191 quad_perm:[1,0,3,2] row_mask:0xf bank_mask:0xf
	v_add_f32_dpp v184, v184, v184 quad_perm:[2,3,0,1] row_mask:0xf bank_mask:0xf
	v_add_f32_dpp v185, v185, v185 quad_perm:[2,3,0,1] row_mask:0xf bank_mask:0xf
	v_add_f32_dpp v186, v186, v186 quad_perm:[2,3,0,1] row_mask:0xf bank_mask:0xf
	v_add_f32_dpp v187, v187, v187 quad_perm:[2,3,0,1] row_mask:0xf bank_mask:0xf
	v_add_f32_dpp v188, v188, v188 quad_perm:[2,3,0,1] row_mask:0xf bank_mask:0xf
	v_add_f32_dpp v189, v189, v189 quad_perm:[2,3,0,1] row_mask:0xf bank_mask:0xf
	v_add_f32_dpp v190, v190, v190 quad_perm:[2,3,0,1] row_mask:0xf bank_mask:0xf
	v_add_f32_dpp v191, v191, v191 quad_perm:[2,3,0,1] row_mask:0xf bank_mask:0xf
	v_add_f32_dpp v184, v184, v184 row_half_mirror row_mask:0xf bank_mask:0xf
	v_add_f32_dpp v185, v185, v185 row_half_mirror row_mask:0xf bank_mask:0xf
	v_add_f32_dpp v186, v186, v186 row_half_mirror row_mask:0xf bank_mask:0xf
	v_add_f32_dpp v187, v187, v187 row_half_mirror row_mask:0xf bank_mask:0xf
	v_add_f32_dpp v188, v188, v188 row_half_mirror row_mask:0xf bank_mask:0xf
	v_add_f32_dpp v189, v189, v189 row_half_mirror row_mask:0xf bank_mask:0xf
	v_add_f32_dpp v190, v190, v190 row_half_mirror row_mask:0xf bank_mask:0xf
	v_add_f32_dpp v191, v191, v191 row_half_mirror row_mask:0xf bank_mask:0xf
	v_add_f32_dpp v184, v184, v184 row_mirror row_mask:0xf bank_mask:0xf
	v_add_f32_dpp v185, v185, v185 row_mirror row_mask:0xf bank_mask:0xf
	v_add_f32_dpp v186, v186, v186 row_mirror row_mask:0xf bank_mask:0xf
	v_add_f32_dpp v187, v187, v187 row_mirror row_mask:0xf bank_mask:0xf
	v_add_f32_dpp v188, v188, v188 row_mirror row_mask:0xf bank_mask:0xf
	v_add_f32_dpp v189, v189, v189 row_mirror row_mask:0xf bank_mask:0xf
	v_add_f32_dpp v190, v190, v190 row_mirror row_mask:0xf bank_mask:0xf
	v_add_f32_dpp v191, v191, v191 row_mirror row_mask:0xf bank_mask:0xf
	v_cmp_eq_u32_e32 vcc, 0, v192
	s_and_saveexec_b64 s[0:1], vcc
	global_store_dword v194, v184, s[28:29]
	s_add_u32 s28, s28, 0x100
	s_addc_u32 s29, s29, 0
	global_store_dword v194, v185, s[28:29]
	s_add_u32 s28, s28, 0x100
	s_addc_u32 s29, s29, 0
	global_store_dword v194, v186, s[28:29]
	s_add_u32 s28, s28, 0x100
	s_addc_u32 s29, s29, 0
	global_store_dword v194, v187, s[28:29]
	s_add_u32 s28, s28, 0x100
	s_addc_u32 s29, s29, 0
	global_store_dword v194, v188, s[28:29]
	s_add_u32 s28, s28, 0x100
	s_addc_u32 s29, s29, 0
	global_store_dword v194, v189, s[28:29]
	s_add_u32 s28, s28, 0x100
	s_addc_u32 s29, s29, 0
	global_store_dword v194, v190, s[28:29]
	s_add_u32 s28, s28, 0x100
	s_addc_u32 s29, s29, 0
	global_store_dword v194, v191, s[28:29]
	s_add_u32 s28, s28, 0x100
	s_addc_u32 s29, s29, 0
	s_or_b64 exec, exec, s[0:1]
	ds_write2_b32 v130, v18, v2 offset0:0 offset1:32
	ds_write2_b32 v130, v19, v3 offset0:68 offset1:100
	ds_write2_b32 v130, v20, v4 offset0:136 offset1:168
	ds_write2_b32 v130, v21, v5 offset0:204 offset1:236
	v_add_u32_e32 v130, 0x880, v130
	ds_write2_b32 v130, v22, v6 offset0:0 offset1:32
	ds_write2_b32 v130, v23, v7 offset0:68 offset1:100
	ds_write2_b32 v130, v24, v8 offset0:136 offset1:168
	ds_write2_b32 v130, v25, v9 offset0:204 offset1:236
	v_add_u32_e32 v130, 0x880, v130
	ds_write2_b32 v130, v26, v10 offset0:0 offset1:32
	ds_write2_b32 v130, v27, v11 offset0:68 offset1:100
	ds_write2_b32 v130, v28, v12 offset0:136 offset1:168
	ds_write2_b32 v130, v29, v13 offset0:204 offset1:236
	v_add_u32_e32 v130, 0x880, v130
	ds_write2_b32 v130, v30, v14 offset0:0 offset1:32
	ds_write2_b32 v130, v31, v15 offset0:68 offset1:100
	ds_write2_b32 v130, v32, v16 offset0:136 offset1:168
	ds_write2_b32 v130, v33, v17 offset0:204 offset1:236
	v_subrev_u32_e32 v130, 0x1980, v130
	ds_read_b128 v[132:135], v131
	ds_read_b128 v[136:139], v131 offset:1088
	ds_read_b128 v[140:143], v131 offset:2176
	ds_read_b128 v[144:147], v131 offset:3264
	ds_read_b128 v[18:21], v131 offset:4352
	ds_read_b128 v[22:25], v131 offset:5440
	ds_read_b128 v[26:29], v131 offset:6528
	ds_read_b128 v[30:33], v131 offset:7616
	s_waitcnt vmcnt(8) lgkmcnt(0)
	v_fma_f32 v132, v132, v180, v148
	v_fma_f32 v133, v133, v181, v149
	v_fma_f32 v134, v134, v182, v150
	v_fma_f32 v135, v135, v183, v151
	global_store_dwordx4 v0, v[132:135], s[38:39] nt
	s_add_u32 s38, s38, 0x4000
	s_addc_u32 s39, s39, 0
	v_mul_f32_e32 v184, v132, v132
	v_fmac_f32_e32 v184, v133, v133
	v_fmac_f32_e32 v184, v134, v134
	v_fmac_f32_e32 v184, v135, v135
	v_fma_f32 v136, v136, v180, v152
	v_fma_f32 v137, v137, v181, v153
	v_fma_f32 v138, v138, v182, v154
	v_fma_f32 v139, v139, v183, v155
	global_store_dwordx4 v0, v[136:139], s[38:39] nt
	s_add_u32 s38, s38, 0x4000
	s_addc_u32 s39, s39, 0
	v_mul_f32_e32 v185, v136, v136
	v_fmac_f32_e32 v185, v137, v137
	v_fmac_f32_e32 v185, v138, v138
	v_fmac_f32_e32 v185, v139, v139
	v_fma_f32 v140, v140, v180, v156
	v_fma_f32 v141, v141, v181, v157
	v_fma_f32 v142, v142, v182, v158
	v_fma_f32 v143, v143, v183, v159
	global_store_dwordx4 v0, v[140:143], s[38:39] nt
	s_add_u32 s38, s38, 0x4000
	s_addc_u32 s39, s39, 0
	v_mul_f32_e32 v186, v140, v140
	v_fmac_f32_e32 v186, v141, v141
	v_fmac_f32_e32 v186, v142, v142
	v_fmac_f32_e32 v186, v143, v143
	v_fma_f32 v144, v144, v180, v160
	v_fma_f32 v145, v145, v181, v161
	v_fma_f32 v146, v146, v182, v162
	v_fma_f32 v147, v147, v183, v163
	global_store_dwordx4 v0, v[144:147], s[38:39] nt
	s_add_u32 s38, s38, 0x4000
	s_addc_u32 s39, s39, 0
	v_mul_f32_e32 v187, v144, v144
	v_fmac_f32_e32 v187, v145, v145
	v_fmac_f32_e32 v187, v146, v146
	v_fmac_f32_e32 v187, v147, v147
	v_fma_f32 v18, v18, v180, v164
	v_fma_f32 v19, v19, v181, v165
	v_fma_f32 v20, v20, v182, v166
	v_fma_f32 v21, v21, v183, v167
	global_store_dwordx4 v0, v[18:21], s[38:39] nt
	s_add_u32 s38, s38, 0x4000
	s_addc_u32 s39, s39, 0
	v_mul_f32_e32 v188, v18, v18
	v_fmac_f32_e32 v188, v19, v19
	v_fmac_f32_e32 v188, v20, v20
	v_fmac_f32_e32 v188, v21, v21
	v_fma_f32 v22, v22, v180, v168
	v_fma_f32 v23, v23, v181, v169
	v_fma_f32 v24, v24, v182, v170
	v_fma_f32 v25, v25, v183, v171
	global_store_dwordx4 v0, v[22:25], s[38:39] nt
	s_add_u32 s38, s38, 0x4000
	s_addc_u32 s39, s39, 0
	v_mul_f32_e32 v189, v22, v22
	v_fmac_f32_e32 v189, v23, v23
	v_fmac_f32_e32 v189, v24, v24
	v_fmac_f32_e32 v189, v25, v25
	v_fma_f32 v26, v26, v180, v172
	v_fma_f32 v27, v27, v181, v173
	v_fma_f32 v28, v28, v182, v174
	v_fma_f32 v29, v29, v183, v175
	global_store_dwordx4 v0, v[26:29], s[38:39] nt
	s_add_u32 s38, s38, 0x4000
	s_addc_u32 s39, s39, 0
	v_mul_f32_e32 v190, v26, v26
	v_fmac_f32_e32 v190, v27, v27
	v_fmac_f32_e32 v190, v28, v28
	v_fmac_f32_e32 v190, v29, v29
	v_fma_f32 v30, v30, v180, v176
	v_fma_f32 v31, v31, v181, v177
	v_fma_f32 v32, v32, v182, v178
	v_fma_f32 v33, v33, v183, v179
	global_store_dwordx4 v0, v[30:33], s[38:39] nt
	s_add_u32 s38, s38, 0x4000
	s_addc_u32 s39, s39, 0
	v_mul_f32_e32 v191, v30, v30
	v_fmac_f32_e32 v191, v31, v31
	v_fmac_f32_e32 v191, v32, v32
	v_fmac_f32_e32 v191, v33, v33
	v_add_f32_dpp v184, v184, v184 quad_perm:[1,0,3,2] row_mask:0xf bank_mask:0xf
	v_add_f32_dpp v185, v185, v185 quad_perm:[1,0,3,2] row_mask:0xf bank_mask:0xf
	v_add_f32_dpp v186, v186, v186 quad_perm:[1,0,3,2] row_mask:0xf bank_mask:0xf
	v_add_f32_dpp v187, v187, v187 quad_perm:[1,0,3,2] row_mask:0xf bank_mask:0xf
	v_add_f32_dpp v188, v188, v188 quad_perm:[1,0,3,2] row_mask:0xf bank_mask:0xf
	v_add_f32_dpp v189, v189, v189 quad_perm:[1,0,3,2] row_mask:0xf bank_mask:0xf
	v_add_f32_dpp v190, v190, v190 quad_perm:[1,0,3,2] row_mask:0xf bank_mask:0xf
	v_add_f32_dpp v191, v191, v191 quad_perm:[1,0,3,2] row_mask:0xf bank_mask:0xf
	v_add_f32_dpp v184, v184, v184 quad_perm:[2,3,0,1] row_mask:0xf bank_mask:0xf
	v_add_f32_dpp v185, v185, v185 quad_perm:[2,3,0,1] row_mask:0xf bank_mask:0xf
	v_add_f32_dpp v186, v186, v186 quad_perm:[2,3,0,1] row_mask:0xf bank_mask:0xf
	v_add_f32_dpp v187, v187, v187 quad_perm:[2,3,0,1] row_mask:0xf bank_mask:0xf
	v_add_f32_dpp v188, v188, v188 quad_perm:[2,3,0,1] row_mask:0xf bank_mask:0xf
	v_add_f32_dpp v189, v189, v189 quad_perm:[2,3,0,1] row_mask:0xf bank_mask:0xf
	v_add_f32_dpp v190, v190, v190 quad_perm:[2,3,0,1] row_mask:0xf bank_mask:0xf
	v_add_f32_dpp v191, v191, v191 quad_perm:[2,3,0,1] row_mask:0xf bank_mask:0xf
	v_add_f32_dpp v184, v184, v184 row_half_mirror row_mask:0xf bank_mask:0xf
	v_add_f32_dpp v185, v185, v185 row_half_mirror row_mask:0xf bank_mask:0xf
	v_add_f32_dpp v186, v186, v186 row_half_mirror row_mask:0xf bank_mask:0xf
	v_add_f32_dpp v187, v187, v187 row_half_mirror row_mask:0xf bank_mask:0xf
	v_add_f32_dpp v188, v188, v188 row_half_mirror row_mask:0xf bank_mask:0xf
	v_add_f32_dpp v189, v189, v189 row_half_mirror row_mask:0xf bank_mask:0xf
	v_add_f32_dpp v190, v190, v190 row_half_mirror row_mask:0xf bank_mask:0xf
	v_add_f32_dpp v191, v191, v191 row_half_mirror row_mask:0xf bank_mask:0xf
	v_add_f32_dpp v184, v184, v184 row_mirror row_mask:0xf bank_mask:0xf
	v_add_f32_dpp v185, v185, v185 row_mirror row_mask:0xf bank_mask:0xf
	v_add_f32_dpp v186, v186, v186 row_mirror row_mask:0xf bank_mask:0xf
	v_add_f32_dpp v187, v187, v187 row_mirror row_mask:0xf bank_mask:0xf
	v_add_f32_dpp v188, v188, v188 row_mirror row_mask:0xf bank_mask:0xf
	v_add_f32_dpp v189, v189, v189 row_mirror row_mask:0xf bank_mask:0xf
	v_add_f32_dpp v190, v190, v190 row_mirror row_mask:0xf bank_mask:0xf
	v_add_f32_dpp v191, v191, v191 row_mirror row_mask:0xf bank_mask:0xf
	v_cmp_eq_u32_e32 vcc, 0, v192
	s_and_saveexec_b64 s[0:1], vcc
	global_store_dword v194, v184, s[28:29]
	s_add_u32 s28, s28, 0x100
	s_addc_u32 s29, s29, 0
	global_store_dword v194, v185, s[28:29]
	s_add_u32 s28, s28, 0x100
	s_addc_u32 s29, s29, 0
	global_store_dword v194, v186, s[28:29]
	s_add_u32 s28, s28, 0x100
	s_addc_u32 s29, s29, 0
	global_store_dword v194, v187, s[28:29]
	s_add_u32 s28, s28, 0x100
	s_addc_u32 s29, s29, 0
	global_store_dword v194, v188, s[28:29]
	s_add_u32 s28, s28, 0x100
	s_addc_u32 s29, s29, 0
	global_store_dword v194, v189, s[28:29]
	s_add_u32 s28, s28, 0x100
	s_addc_u32 s29, s29, 0
	global_store_dword v194, v190, s[28:29]
	s_add_u32 s28, s28, 0x100
	s_addc_u32 s29, s29, 0
	global_store_dword v194, v191, s[28:29]
	s_add_u32 s28, s28, 0x100
	s_addc_u32 s29, s29, 0
	s_or_b64 exec, exec, s[0:1]
	s_add_i32 s34, s34, s30
	s_cmp_ge_i32 s34, s35
	s_cbranch_scc0 .LBB0_52
